# LDS-DMA attention staging: DMA issue interleaved with the first S-chain MFMAs of the tile
# speedup vs baseline: 1.0065x; 1.0065x over previous
.Lattn_nf_loop:
	ds_read_b128 v[98:101], v82 offset:0
	ds_read_b128 v[102:105], v83 offset:0
	ds_read_b128 v[106:109], v84 offset:0
	ds_read_b128 v[110:113], v85 offset:0
	s_and_b32 s10, s15, 1
	s_xor_b32 s10, s10, 1
	s_lshl_b32 s10, s10, 15
	s_add_i32 s10, s10, s11
	s_add_i32 s6, s10, 0x10000
	s_waitcnt lgkmcnt(3)
	v_mfma_f32_32x32x16_bf16 v[138:153], v[98:101], v[10:13], 0
	ds_read_b128 v[98:101], v82 offset:8192
	s_add_i32 m0, s10, 0x0
	s_nop 0
	global_load_lds_dwordx4 v124, s[64:65]
	s_add_i32 m0, s10, 0x2000
	s_nop 0
	global_load_lds_dwordx4 v124, s[66:67]
	s_waitcnt lgkmcnt(3)
	v_mfma_f32_32x32x16_bf16 v[138:153], v[102:105], v[14:17], v[138:153]
	ds_read_b128 v[102:105], v83 offset:8192
	s_add_i32 m0, s10, 0x4000
	s_nop 0
	global_load_lds_dwordx4 v124, s[68:69]
	s_add_i32 m0, s10, 0x6000
	s_nop 0
	global_load_lds_dwordx4 v124, s[70:71]
	v_add_u32_e32 v124, s36, v124
	s_waitcnt lgkmcnt(3)
	v_mfma_f32_32x32x16_bf16 v[138:153], v[106:109], v[2:5], v[138:153]
	ds_read_b128 v[106:109], v84 offset:8192
	s_add_i32 m0, s6, 0x0
	s_nop 0
	global_load_lds_dwordx4 v125, s[72:73]
	s_add_i32 m0, s6, 0x2000
	s_nop 0
	global_load_lds_dwordx4 v125, s[74:75]
	s_waitcnt lgkmcnt(3)
	v_mfma_f32_32x32x16_bf16 v[138:153], v[110:113], v[6:9], v[138:153]
	ds_read_b128 v[110:113], v85 offset:8192
	s_add_i32 m0, s6, 0x4000
	s_nop 0
	global_load_lds_dwordx4 v125, s[76:77]
	s_add_i32 m0, s6, 0x6000
	s_nop 0
	global_load_lds_dwordx4 v125, s[78:79]
	v_add_u32_e32 v125, s38, v125
	ds_read_b128 v[128:131], v86 offset:0
	ds_read_b128 v[184:187], v86 offset:8192
	ds_read_b128 v[188:191], v86 offset:16384
	ds_read_b128 v[192:195], v86 offset:24576
	s_waitcnt lgkmcnt(7)
	v_mfma_f32_32x32x16_bf16 v[154:169], v[98:101], v[10:13], 0
	ds_read_b128 v[98:101], v82 offset:16384
	v_exp_f32_e32 v138, v138
	v_exp_f32_e32 v139, v139
	v_exp_f32_e32 v140, v140
	v_exp_f32_e32 v141, v141
	v_exp_f32_e32 v142, v142
	v_exp_f32_e32 v143, v143
	s_waitcnt lgkmcnt(7)
	v_mfma_f32_32x32x16_bf16 v[154:169], v[102:105], v[14:17], v[154:169]
	ds_read_b128 v[102:105], v83 offset:16384
	v_exp_f32_e32 v144, v144
	v_exp_f32_e32 v145, v145
	v_add_f32_e32 v122, v138, v122
	v_add_f32_e32 v122, v139, v122
	v_add_f32_e32 v122, v140, v122
	v_add_f32_e32 v122, v141, v122
	v_add_f32_e32 v122, v142, v122
	v_add_f32_e32 v122, v143, v122
	v_add_f32_e32 v122, v144, v122
	v_add_f32_e32 v122, v145, v122
	v_cvt_pk_bf16_f32 v114, v138, v139
	v_cvt_pk_bf16_f32 v115, v140, v141
	v_cvt_pk_bf16_f32 v116, v142, v143
	v_cvt_pk_bf16_f32 v117, v144, v145
	ds_read_b128 v[196:199], v87 offset:0
	ds_read_b128 v[216:219], v87 offset:8192
	ds_read_b128 v[200:203], v87 offset:16384
	ds_read_b128 v[204:207], v87 offset:24576
	s_waitcnt lgkmcnt(11)
	v_mfma_f32_32x32x16_bf16 v[154:169], v[106:109], v[2:5], v[154:169]
	ds_read_b128 v[106:109], v84 offset:16384
	v_exp_f32_e32 v146, v146
	v_exp_f32_e32 v147, v147
	s_waitcnt lgkmcnt(11)
	v_mfma_f32_32x32x16_bf16 v[154:169], v[110:113], v[6:9], v[154:169]
	ds_read_b128 v[110:113], v85 offset:16384
	v_exp_f32_e32 v148, v148
	v_exp_f32_e32 v149, v149
	s_waitcnt lgkmcnt(11)
	v_mfma_f32_32x32x16_bf16 v[18:33], v[128:131], v[114:117], v[18:33]
	v_exp_f32_e32 v150, v150
	v_exp_f32_e32 v151, v151
	s_waitcnt lgkmcnt(10)
	v_mfma_f32_32x32x16_bf16 v[34:49], v[184:187], v[114:117], v[34:49]
	v_exp_f32_e32 v152, v152
	v_exp_f32_e32 v153, v153
	s_waitcnt lgkmcnt(9)
	v_mfma_f32_32x32x16_bf16 v[50:65], v[188:191], v[114:117], v[50:65]
	v_add_f32_e32 v122, v146, v122
	v_add_f32_e32 v122, v147, v122
	v_add_f32_e32 v122, v148, v122
	v_add_f32_e32 v122, v149, v122
	s_waitcnt lgkmcnt(8)
	v_mfma_f32_32x32x16_bf16 v[66:81], v[192:195], v[114:117], v[66:81]
	v_add_f32_e32 v122, v150, v122
	v_add_f32_e32 v122, v151, v122
	v_add_f32_e32 v122, v152, v122
	v_add_f32_e32 v122, v153, v122
	v_cvt_pk_bf16_f32 v118, v146, v147
	v_cvt_pk_bf16_f32 v119, v148, v149
	v_cvt_pk_bf16_f32 v120, v150, v151
	v_cvt_pk_bf16_f32 v121, v152, v153
	ds_read_b128 v[128:131], v88 offset:0
	ds_read_b128 v[184:187], v88 offset:8192
	ds_read_b128 v[188:191], v88 offset:16384
	ds_read_b128 v[192:195], v88 offset:24576
	s_waitcnt lgkmcnt(11)
	v_mfma_f32_32x32x16_bf16 v[138:153], v[98:101], v[10:13], 0
	ds_read_b128 v[98:101], v82 offset:24576
	v_exp_f32_e32 v154, v154
	v_exp_f32_e32 v155, v155
	s_waitcnt lgkmcnt(11)
	v_mfma_f32_32x32x16_bf16 v[138:153], v[102:105], v[14:17], v[138:153]
	ds_read_b128 v[102:105], v83 offset:24576
	v_exp_f32_e32 v156, v156
	v_exp_f32_e32 v157, v157
	s_waitcnt lgkmcnt(11)
	v_mfma_f32_32x32x16_bf16 v[18:33], v[196:199], v[118:121], v[18:33]
	v_exp_f32_e32 v158, v158
	v_exp_f32_e32 v159, v159
	s_waitcnt lgkmcnt(10)
	v_mfma_f32_32x32x16_bf16 v[34:49], v[216:219], v[118:121], v[34:49]
	v_exp_f32_e32 v160, v160
	v_exp_f32_e32 v161, v161
	s_waitcnt lgkmcnt(9)
	v_mfma_f32_32x32x16_bf16 v[50:65], v[200:203], v[118:121], v[50:65]
	v_add_f32_e32 v122, v154, v122
	v_add_f32_e32 v122, v155, v122
	v_add_f32_e32 v122, v156, v122
	v_add_f32_e32 v122, v157, v122
	s_waitcnt lgkmcnt(8)
	v_mfma_f32_32x32x16_bf16 v[66:81], v[204:207], v[118:121], v[66:81]
	v_add_f32_e32 v122, v158, v122
	v_add_f32_e32 v122, v159, v122
	v_add_f32_e32 v122, v160, v122
	v_add_f32_e32 v122, v161, v122
	v_cvt_pk_bf16_f32 v114, v154, v155
	v_cvt_pk_bf16_f32 v115, v156, v157
	v_cvt_pk_bf16_f32 v116, v158, v159
	v_cvt_pk_bf16_f32 v117, v160, v161
	ds_read_b128 v[196:199], v89 offset:0
	ds_read_b128 v[216:219], v89 offset:8192
	ds_read_b128 v[200:203], v89 offset:16384
	ds_read_b128 v[204:207], v89 offset:24576
	s_waitcnt lgkmcnt(11)
	v_mfma_f32_32x32x16_bf16 v[138:153], v[106:109], v[2:5], v[138:153]
	ds_read_b128 v[106:109], v84 offset:24576
	v_exp_f32_e32 v162, v162
	v_exp_f32_e32 v163, v163
	s_waitcnt lgkmcnt(11)
	v_mfma_f32_32x32x16_bf16 v[138:153], v[110:113], v[6:9], v[138:153]
	ds_read_b128 v[110:113], v85 offset:24576
	v_exp_f32_e32 v164, v164
	v_exp_f32_e32 v165, v165
	s_waitcnt lgkmcnt(11)
	v_mfma_f32_32x32x16_bf16 v[18:33], v[128:131], v[114:117], v[18:33]
	v_exp_f32_e32 v166, v166
	v_exp_f32_e32 v167, v167
	s_waitcnt lgkmcnt(10)
	v_mfma_f32_32x32x16_bf16 v[34:49], v[184:187], v[114:117], v[34:49]
	v_exp_f32_e32 v168, v168
	v_exp_f32_e32 v169, v169
	s_waitcnt lgkmcnt(9)
	v_mfma_f32_32x32x16_bf16 v[50:65], v[188:191], v[114:117], v[50:65]
	v_add_f32_e32 v122, v162, v122
	v_add_f32_e32 v122, v163, v122
	v_add_f32_e32 v122, v164, v122
	v_add_f32_e32 v122, v165, v122
	s_waitcnt lgkmcnt(8)
	v_mfma_f32_32x32x16_bf16 v[66:81], v[192:195], v[114:117], v[66:81]
	v_add_f32_e32 v122, v166, v122
	v_add_f32_e32 v122, v167, v122
	v_add_f32_e32 v122, v168, v122
	v_add_f32_e32 v122, v169, v122
	v_cvt_pk_bf16_f32 v118, v162, v163
	v_cvt_pk_bf16_f32 v119, v164, v165
	v_cvt_pk_bf16_f32 v120, v166, v167
	v_cvt_pk_bf16_f32 v121, v168, v169
	ds_read_b128 v[128:131], v90 offset:0
	ds_read_b128 v[184:187], v90 offset:8192
	ds_read_b128 v[188:191], v90 offset:16384
	ds_read_b128 v[192:195], v90 offset:24576
	s_waitcnt lgkmcnt(11)
	v_mfma_f32_32x32x16_bf16 v[154:169], v[98:101], v[10:13], 0
	v_exp_f32_e32 v138, v138
	v_exp_f32_e32 v139, v139
	s_waitcnt lgkmcnt(10)
	v_mfma_f32_32x32x16_bf16 v[154:169], v[102:105], v[14:17], v[154:169]
	v_exp_f32_e32 v140, v140
	v_exp_f32_e32 v141, v141
	s_waitcnt lgkmcnt(9)
	v_mfma_f32_32x32x16_bf16 v[18:33], v[196:199], v[118:121], v[18:33]
	v_exp_f32_e32 v142, v142
	v_exp_f32_e32 v143, v143
	s_waitcnt lgkmcnt(8)
	v_mfma_f32_32x32x16_bf16 v[34:49], v[216:219], v[118:121], v[34:49]
	v_exp_f32_e32 v144, v144
	v_exp_f32_e32 v145, v145
	s_waitcnt lgkmcnt(7)
	v_mfma_f32_32x32x16_bf16 v[50:65], v[200:203], v[118:121], v[50:65]
	v_add_f32_e32 v122, v138, v122
	v_add_f32_e32 v122, v139, v122
	v_add_f32_e32 v122, v140, v122
	v_add_f32_e32 v122, v141, v122
	s_waitcnt lgkmcnt(6)
	v_mfma_f32_32x32x16_bf16 v[66:81], v[204:207], v[118:121], v[66:81]
	v_add_f32_e32 v122, v142, v122
	v_add_f32_e32 v122, v143, v122
	v_add_f32_e32 v122, v144, v122
	v_add_f32_e32 v122, v145, v122
	v_cvt_pk_bf16_f32 v114, v138, v139
	v_cvt_pk_bf16_f32 v115, v140, v141
	v_cvt_pk_bf16_f32 v116, v142, v143
	v_cvt_pk_bf16_f32 v117, v144, v145
	ds_read_b128 v[196:199], v91 offset:0
	ds_read_b128 v[216:219], v91 offset:8192
	ds_read_b128 v[200:203], v91 offset:16384
	ds_read_b128 v[204:207], v91 offset:24576
	s_waitcnt lgkmcnt(9)
	v_mfma_f32_32x32x16_bf16 v[154:169], v[106:109], v[2:5], v[154:169]
	v_exp_f32_e32 v146, v146
	v_exp_f32_e32 v147, v147
	s_waitcnt lgkmcnt(8)
	v_mfma_f32_32x32x16_bf16 v[154:169], v[110:113], v[6:9], v[154:169]
	v_exp_f32_e32 v148, v148
	v_exp_f32_e32 v149, v149
	s_waitcnt lgkmcnt(7)
	v_mfma_f32_32x32x16_bf16 v[18:33], v[128:131], v[114:117], v[18:33]
	v_exp_f32_e32 v150, v150
	v_exp_f32_e32 v151, v151
	s_waitcnt lgkmcnt(6)
	v_mfma_f32_32x32x16_bf16 v[34:49], v[184:187], v[114:117], v[34:49]
	v_exp_f32_e32 v152, v152
	v_exp_f32_e32 v153, v153
	s_waitcnt lgkmcnt(5)
	v_mfma_f32_32x32x16_bf16 v[50:65], v[188:191], v[114:117], v[50:65]
	v_add_f32_e32 v122, v146, v122
	v_add_f32_e32 v122, v147, v122
	v_add_f32_e32 v122, v148, v122
	v_add_f32_e32 v122, v149, v122
	s_waitcnt lgkmcnt(4)
	v_mfma_f32_32x32x16_bf16 v[66:81], v[192:195], v[114:117], v[66:81]
	v_add_f32_e32 v122, v150, v122
	v_add_f32_e32 v122, v151, v122
	v_add_f32_e32 v122, v152, v122
	v_add_f32_e32 v122, v153, v122
	v_cvt_pk_bf16_f32 v118, v146, v147
	v_cvt_pk_bf16_f32 v119, v148, v149
	v_cvt_pk_bf16_f32 v120, v150, v151
	v_cvt_pk_bf16_f32 v121, v152, v153
	ds_read_b128 v[128:131], v92 offset:0
	ds_read_b128 v[184:187], v92 offset:8192
	ds_read_b128 v[188:191], v92 offset:16384
	ds_read_b128 v[192:195], v92 offset:24576
	s_waitcnt lgkmcnt(7)
	v_mfma_f32_32x32x16_bf16 v[18:33], v[196:199], v[118:121], v[18:33]
	v_exp_f32_e32 v154, v154
	v_exp_f32_e32 v155, v155
	v_exp_f32_e32 v156, v156
	s_waitcnt lgkmcnt(6)
	v_mfma_f32_32x32x16_bf16 v[34:49], v[216:219], v[118:121], v[34:49]
	v_exp_f32_e32 v157, v157
	v_exp_f32_e32 v158, v158
	v_exp_f32_e32 v159, v159
	s_waitcnt lgkmcnt(5)
	v_mfma_f32_32x32x16_bf16 v[50:65], v[200:203], v[118:121], v[50:65]
	v_exp_f32_e32 v160, v160
	v_exp_f32_e32 v161, v161
	v_add_f32_e32 v122, v154, v122
	v_add_f32_e32 v122, v155, v122
	s_waitcnt lgkmcnt(4)
	v_mfma_f32_32x32x16_bf16 v[66:81], v[204:207], v[118:121], v[66:81]
	v_add_f32_e32 v122, v156, v122
	v_add_f32_e32 v122, v157, v122
	v_add_f32_e32 v122, v158, v122
	v_add_f32_e32 v122, v159, v122
	v_add_f32_e32 v122, v160, v122
	v_add_f32_e32 v122, v161, v122
	v_cvt_pk_bf16_f32 v114, v154, v155
	v_cvt_pk_bf16_f32 v115, v156, v157
	v_cvt_pk_bf16_f32 v116, v158, v159
	v_cvt_pk_bf16_f32 v117, v160, v161
	ds_read_b128 v[196:199], v93 offset:0
	ds_read_b128 v[216:219], v93 offset:8192
	ds_read_b128 v[200:203], v93 offset:16384
	ds_read_b128 v[204:207], v93 offset:24576
	s_waitcnt lgkmcnt(7)
	v_mfma_f32_32x32x16_bf16 v[18:33], v[128:131], v[114:117], v[18:33]
	v_exp_f32_e32 v162, v162
	v_exp_f32_e32 v163, v163
	v_exp_f32_e32 v164, v164
	s_waitcnt lgkmcnt(6)
	v_mfma_f32_32x32x16_bf16 v[34:49], v[184:187], v[114:117], v[34:49]
	v_exp_f32_e32 v165, v165
	v_exp_f32_e32 v166, v166
	v_exp_f32_e32 v167, v167
	s_waitcnt lgkmcnt(5)
	v_mfma_f32_32x32x16_bf16 v[50:65], v[188:191], v[114:117], v[50:65]
	v_exp_f32_e32 v168, v168
	v_exp_f32_e32 v169, v169
	v_add_f32_e32 v122, v162, v122
	v_add_f32_e32 v122, v163, v122
	s_waitcnt lgkmcnt(4)
	v_mfma_f32_32x32x16_bf16 v[66:81], v[192:195], v[114:117], v[66:81]
	v_add_f32_e32 v122, v164, v122
	v_add_f32_e32 v122, v165, v122
	v_add_f32_e32 v122, v166, v122
	v_add_f32_e32 v122, v167, v122
	v_add_f32_e32 v122, v168, v122
	v_add_f32_e32 v122, v169, v122
	v_cvt_pk_bf16_f32 v118, v162, v163
	v_cvt_pk_bf16_f32 v119, v164, v165
	v_cvt_pk_bf16_f32 v120, v166, v167
	v_cvt_pk_bf16_f32 v121, v168, v169
	s_waitcnt lgkmcnt(3)
	s_nop 0
	v_mfma_f32_32x32x16_bf16 v[18:33], v[196:199], v[118:121], v[18:33]
	s_waitcnt lgkmcnt(2)
	v_mfma_f32_32x32x16_bf16 v[34:49], v[216:219], v[118:121], v[34:49]
	s_waitcnt lgkmcnt(1)
	v_mfma_f32_32x32x16_bf16 v[50:65], v[200:203], v[118:121], v[50:65]
	s_waitcnt lgkmcnt(0)
	v_mfma_f32_32x32x16_bf16 v[66:81], v[204:207], v[118:121], v[66:81]
	v_xor_b32_e32 v82, 0x8000, v82
	v_xor_b32_e32 v83, 0x8000, v83
	v_xor_b32_e32 v84, 0x8000, v84
	v_xor_b32_e32 v85, 0x8000, v85
	v_xor_b32_e32 v86, 0x8000, v86
	v_xor_b32_e32 v87, 0x8000, v87
	v_xor_b32_e32 v88, 0x8000, v88
	v_xor_b32_e32 v89, 0x8000, v89
	v_xor_b32_e32 v90, 0x8000, v90
	v_xor_b32_e32 v91, 0x8000, v91
	v_xor_b32_e32 v92, 0x8000, v92
	v_xor_b32_e32 v93, 0x8000, v93
	s_waitcnt vmcnt(0)
	s_waitcnt lgkmcnt(0)
	s_barrier
	s_add_i32 s15, s15, 1
	s_cmp_eq_u32 s15, 34
	s_cbranch_scc0 .Lattn_nf_loop
	v_readlane_b32 s64, v175, 0
	v_readlane_b32 s65, v175, 1
	v_readlane_b32 s66, v175, 2
	v_readlane_b32 s67, v175, 3
	v_readlane_b32 s68, v175, 4
	v_readlane_b32 s69, v175, 5
	v_readlane_b32 s70, v175, 6
	v_readlane_b32 s71, v175, 7
	v_readlane_b32 s72, v175, 8
	v_readlane_b32 s73, v175, 9
	v_readlane_b32 s74, v175, 10
	v_readlane_b32 s75, v175, 11
	v_readlane_b32 s76, v175, 12
	v_readlane_b32 s77, v175, 13
	v_readlane_b32 s78, v175, 14
	v_readlane_b32 s79, v175, 15
	s_nop 4
	s_mov_b32 s10, 0x3fb8aa3b
	s_mov_b32 s11, 0xc2ce8ed0
	s_mov_b32 s6, 0x42b17218
	v_cmp_eq_u32_e64 s[40:41], 0, v179
	s_lshl_b32 s30, s14, 1
	v_lshlrev_b32_e32 v196, 3, v178
	v_mov_b32_e32 v197, 0
	v_lshlrev_b32_e32 v198, 4, v179
	v_or3_b32 v198, v198, v177, v180
	v_ashrrev_i32_e32 v199, 31, v198
	v_lshlrev_b64 v[198:199], 11, v[198:199]
	s_mov_b64 s[100:101], 0x18a10000
	v_lshl_add_u64 v[198:199], s[42:43], 0, v[198:199]
	v_lshl_add_u64 v[198:199], v[198:199], 0, s[30:31]
	v_lshl_add_u64 v[198:199], v[198:199], 0, v[196:197]
	v_lshl_add_u64 v[198:199], v[198:199], 0, s[100:101]
	global_load_dwordx2 v[146:147], v[198:199], off
	global_load_dwordx2 v[148:149], v[198:199], off offset:32
	global_load_dwordx2 v[150:151], v[198:199], off offset:64
	global_load_dwordx2 v[152:153], v[198:199], off offset:96
	global_load_dwordx2 v[188:189], v[198:199], off offset:128
	global_load_dwordx2 v[190:191], v[198:199], off offset:160
	global_load_dwordx2 v[192:193], v[198:199], off offset:192
	global_load_dwordx2 v[194:195], v[198:199], off offset:224
	s_mov_b64 s[100:101], exec
	s_and_b64 exec, exec, s[4:5]
	s_cbranch_execz .Lpop_skip
	v_readlane_b32 s14, v255, 22
	v_readlane_b32 s15, v255, 23
	v_mov_b32_e32 v224, 1
	s_nop 4
	global_atomic_add v224, v0, v224, s[14:15] sc0
